# overlap across segments: odd workgroups run the bandwidth-bound GLA state scan after their windowed-attention items (even ones before), so scan traffic overlaps attention compute
# baseline (speedup 1.0000x reference)
;     __device__ __forceinline__ unsigned char* ws() const { return (unsigned char*)(__attribute__((address_space(1))) unsigned char*)ld(23); }
; __device__ __forceinline__ void gla_scan(const KPD& kp, int tid) {
;     if (tid >= 288) return;
;     const int gid = blockIdx.x * 288 + tid;
;     if (gid >= 2 * 4 * 9216) return;
;     const int e2 = gid % 9216, db = gid / 9216, dir = db >> 2, elem = 2 * e2, h = elem / 4608, d = (elem % 4608) / 96;
;     const bf16* ST = (const bf16*)(kp.ws() + WS_ST) + (size_t)db * NCH * 18432 + elem;
;     bf16* SI = (bf16*)(kp.ws() + WS_SI) + (size_t)db * NCH * 18432 + elem;
;     const float* DEC = (const float*)(kp.ws() + WS_DEC) + (size_t)db * NCH * 192 + h * 48 + d;
.LBB0_352:
	s_or_b64 exec, exec, s[0:1]
	v_mov_b32_e32 v13, v225
	s_movk_i32 s0, 0x120
	s_bitcmp1_b32 s73, 0
	s_cselect_b32 s0, 0, s0
	s_waitcnt lgkmcnt(0)
	s_barrier
	s_nop 0
	v_readfirstlane_b32 s2, v13
	v_cmp_gt_i32_e32 vcc, s0, v13
	s_and_saveexec_b64 s[0:1], vcc
	s_cbranch_execz .LBB0_356
	s_mul_i32 s3, s73, 0x120
	v_add_u32_e32 v2, s3, v13
	s_mov_b32 s3, 0x12000
	v_cmp_gt_i32_e32 vcc, s3, v2
	s_and_b64 exec, exec, vcc
	s_cbranch_execz .LBB0_356
	s_mov_b32 s3, 0x38e38e39
	v_mul_hi_i32 v3, v2, s3
	v_lshrrev_b32_e32 v4, 31, v3
	v_ashrrev_i32_e32 v3, 11, v3
	v_add_u32_e32 v10, v3, v4
	v_mul_i32_i24_e32 v3, 0x2400, v10
	v_sub_u32_e32 v3, v2, v3
	v_lshlrev_b32_e32 v2, 1, v3
	v_mul_i32_i24_e32 v3, 0xe39, v3
	v_lshrrev_b32_e32 v4, 31, v3
	v_ashrrev_i32_e32 v3, 23, v3
	v_add_u16_e32 v8, v3, v4
	v_mul_i32_i24_e32 v3, 0xe39, v2
	v_lshrrev_b32_e32 v4, 31, v3
	v_add_u16_sdwa v3, v3, v4 dst_sel:DWORD dst_unused:UNUSED_PAD src0_sel:BYTE_3 src1_sel:DWORD
	v_mul_lo_u16_e32 v3, 0x1200, v3
	v_sub_u16_e32 v3, v2, v3
	s_movk_i32 s3, 0x2aab
	v_mul_i32_i24_sdwa v3, sext(v3), s3 dst_sel:DWORD dst_unused:UNUSED_PAD src0_sel:WORD_0 src1_sel:DWORD
	v_lshrrev_b32_e32 v4, 31, v3
	v_ashrrev_i32_e32 v3, 20, v3
	v_add_u16_e32 v11, v3, v4
	ds_read_b64 v[4:5], v204
	v_mul_i32_i24_e32 v9, 0x84, v10
	s_mov_b32 s6, 0x9000
	v_ashrrev_i32_e32 v3, 31, v2
	v_lshlrev_b64 v[6:7], 1, v[2:3]
	s_waitcnt lgkmcnt(0)
	v_readfirstlane_b32 s3, v5
	v_readfirstlane_b32 s4, v4
	v_mul_lo_u16_e32 v8, 48, v8
	v_mov_b32_e32 v5, s3
	v_mov_b32_e32 v4, s4
	v_mad_i64_i32 v[4:5], s[4:5], v9, s6, v[4:5]
	v_lshl_add_u64 v[2:3], v[4:5], 0, v[6:7]
	ds_read_b64 v[4:5], v204
	s_mov_b64 s[4:5], 0x15000000
	v_lshl_add_u64 v[2:3], v[2:3], 0, s[4:5]
	v_bfe_i32 v8, v8, 0, 16
	v_cmp_gt_u32_e32 vcc, 4, v10
	s_waitcnt lgkmcnt(0)
	v_readfirstlane_b32 s3, v5
	v_readfirstlane_b32 s4, v4
	s_nop 0
	v_mov_b32_e32 v5, s3
	v_mov_b32_e32 v4, s4
	v_mad_i64_i32 v[4:5], s[4:5], v9, s6, v[4:5]
	v_lshl_add_u64 v[4:5], v[4:5], 0, v[6:7]
	ds_read_b64 v[6:7], v204
	s_mov_b64 s[4:5], 0x1a000000
	v_lshl_add_u64 v[4:5], v[4:5], 0, s[4:5]
	s_waitcnt lgkmcnt(0)
	v_readfirstlane_b32 s3, v7
	v_readfirstlane_b32 s4, v6
	s_nop 0
	v_mov_b32_e32 v7, s3
	s_movk_i32 s3, 0x300
	v_mov_b32_e32 v6, s4
	v_mad_i64_i32 v[6:7], s[4:5], v9, s3, v[6:7]
	v_ashrrev_i32_e32 v9, 31, v8
	v_lshl_add_u64 v[6:7], v[8:9], 2, v[6:7]
	v_bfe_i32 v8, v11, 0, 16
	v_ashrrev_i32_e32 v9, 31, v8
	v_lshl_add_u64 v[6:7], v[8:9], 2, v[6:7]
	s_mov_b64 s[4:5], 0x19b00000
	v_mov_b32_e32 v8, 0
	v_lshl_add_u64 v[6:7], v[6:7], 0, s[4:5]
	s_mov_b32 s4, 0
	s_movk_i32 s3, 0x6e
	v_mov_b32_e32 v9, v8

;     __device__ __forceinline__ unsigned char* ws() const { return (unsigned char*)(__attribute__((address_space(1))) unsigned char*)ld(23); }
; __device__ __forceinline__ void gla_scan(const KPD& kp, int tid) {
;     if (tid >= 288) return;
;     const int gid = blockIdx.x * 288 + tid;
;     if (gid >= 2 * 4 * 9216) return;
;     const int e2 = gid % 9216, db = gid / 9216, dir = db >> 2, elem = 2 * e2, h = elem / 4608, d = (elem % 4608) / 96;
;     const bf16* ST = (const bf16*)(kp.ws() + WS_ST) + (size_t)db * NCH * 18432 + elem;
;     bf16* SI = (bf16*)(kp.ws() + WS_SI) + (size_t)db * NCH * 18432 + elem;
;     const float* DEC = (const float*)(kp.ws() + WS_DEC) + (size_t)db * NCH * 192 + h * 48 + d;
.LBB0_393:
	s_bitcmp1_b32 s73, 0
	s_cbranch_scc0 .Lscan2_skip
	s_mov_b32 s100, s5
	v_mov_b32_e32 v230, v5
	v_mov_b32_e32 v13, v225
	s_movk_i32 s0, 0x120
	s_nop 0
	v_readfirstlane_b32 s2, v13
	v_cmp_gt_i32_e32 vcc, s0, v13
	s_and_saveexec_b64 s[0:1], vcc
	s_cbranch_execz .Lscan2_356
	s_mul_i32 s3, s73, 0x120
	v_add_u32_e32 v2, s3, v13
	s_mov_b32 s3, 0x12000
	v_cmp_gt_i32_e32 vcc, s3, v2
	s_and_b64 exec, exec, vcc
	s_cbranch_execz .Lscan2_356
	s_mov_b32 s3, 0x38e38e39
	v_mul_hi_i32 v3, v2, s3
	v_lshrrev_b32_e32 v4, 31, v3
	v_ashrrev_i32_e32 v3, 11, v3
	v_add_u32_e32 v10, v3, v4
	v_mul_i32_i24_e32 v3, 0x2400, v10
	v_sub_u32_e32 v3, v2, v3
	v_lshlrev_b32_e32 v2, 1, v3
	v_mul_i32_i24_e32 v3, 0xe39, v3
	v_lshrrev_b32_e32 v4, 31, v3
	v_ashrrev_i32_e32 v3, 23, v3
	v_add_u16_e32 v8, v3, v4
	v_mul_i32_i24_e32 v3, 0xe39, v2
	v_lshrrev_b32_e32 v4, 31, v3
	v_add_u16_sdwa v3, v3, v4 dst_sel:DWORD dst_unused:UNUSED_PAD src0_sel:BYTE_3 src1_sel:DWORD
	v_mul_lo_u16_e32 v3, 0x1200, v3
	v_sub_u16_e32 v3, v2, v3
	s_movk_i32 s3, 0x2aab
	v_mul_i32_i24_sdwa v3, sext(v3), s3 dst_sel:DWORD dst_unused:UNUSED_PAD src0_sel:WORD_0 src1_sel:DWORD
	v_lshrrev_b32_e32 v4, 31, v3
	v_ashrrev_i32_e32 v3, 20, v3
	v_add_u16_e32 v11, v3, v4
	ds_read_b64 v[4:5], v204
	v_mul_i32_i24_e32 v9, 0x84, v10
	s_mov_b32 s6, 0x9000
	v_ashrrev_i32_e32 v3, 31, v2
	v_lshlrev_b64 v[6:7], 1, v[2:3]
	s_waitcnt lgkmcnt(0)
	v_readfirstlane_b32 s3, v5
	v_readfirstlane_b32 s4, v4
	v_mul_lo_u16_e32 v8, 48, v8
	v_mov_b32_e32 v5, s3
	v_mov_b32_e32 v4, s4
	v_mad_i64_i32 v[4:5], s[4:5], v9, s6, v[4:5]
	v_lshl_add_u64 v[2:3], v[4:5], 0, v[6:7]
	ds_read_b64 v[4:5], v204
	s_mov_b64 s[4:5], 0x15000000
	v_lshl_add_u64 v[2:3], v[2:3], 0, s[4:5]
	v_bfe_i32 v8, v8, 0, 16
	v_cmp_gt_u32_e32 vcc, 4, v10
	s_waitcnt lgkmcnt(0)
	v_readfirstlane_b32 s3, v5
	v_readfirstlane_b32 s4, v4
	s_nop 0
	v_mov_b32_e32 v5, s3
	v_mov_b32_e32 v4, s4
	v_mad_i64_i32 v[4:5], s[4:5], v9, s6, v[4:5]
	v_lshl_add_u64 v[4:5], v[4:5], 0, v[6:7]
	ds_read_b64 v[6:7], v204
	s_mov_b64 s[4:5], 0x1a000000
	v_lshl_add_u64 v[4:5], v[4:5], 0, s[4:5]
	s_waitcnt lgkmcnt(0)
	v_readfirstlane_b32 s3, v7
	v_readfirstlane_b32 s4, v6
	s_nop 0
	v_mov_b32_e32 v7, s3
	s_movk_i32 s3, 0x300
	v_mov_b32_e32 v6, s4
	v_mad_i64_i32 v[6:7], s[4:5], v9, s3, v[6:7]
	v_ashrrev_i32_e32 v9, 31, v8
	v_lshl_add_u64 v[6:7], v[8:9], 2, v[6:7]
	v_bfe_i32 v8, v11, 0, 16
	v_ashrrev_i32_e32 v9, 31, v8
	v_lshl_add_u64 v[6:7], v[8:9], 2, v[6:7]
	s_mov_b64 s[4:5], 0x19b00000
	v_mov_b32_e32 v8, 0
	v_lshl_add_u64 v[6:7], v[6:7], 0, s[4:5]
	s_mov_b32 s4, 0
	s_movk_i32 s3, 0x6e
	v_mov_b32_e32 v9, v8

;     __device__ __forceinline__ unsigned char* ws() const { return (unsigned char*)(__attribute__((address_space(1))) unsigned char*)ld(23); }
; __device__ __forceinline__ void gla_scan(const KPD& kp, int tid) {
;     if (tid >= 288) return;
;     const int gid = blockIdx.x * 288 + tid;
;     if (gid >= 2 * 4 * 9216) return;
;     const int e2 = gid % 9216, db = gid / 9216, dir = db >> 2, elem = 2 * e2, h = elem / 4608, d = (elem % 4608) / 96;
;     const bf16* ST = (const bf16*)(kp.ws() + WS_ST) + (size_t)db * NCH * 18432 + elem;
;     bf16* SI = (bf16*)(kp.ws() + WS_SI) + (size_t)db * NCH * 18432 + elem;
;     const float* DEC = (const float*)(kp.ws() + WS_DEC) + (size_t)db * NCH * 192 + h * 48 + d;
.Lscan2_356:
	s_or_b64 exec, exec, s[0:1]
	s_mov_b32 s5, s100
	v_mov_b32_e32 v5, v230
